# layer-0 prep x->bf16 rows: a row's four loads in flight together, next row's loads issued before this row's stores (was one load per store-ack round trip)
# speedup vs baseline: 1.0071x; 1.0053x over previous
.LBB0_622:
	s_or_b64 exec, exec, s[2:3]
	s_cmpk_gt_i32 s6, 0x3fff
	s_cbranch_scc1 .LBB0_627
	v_and_b32_e32 v0, 64, v220
	v_add_u32_e32 v0, 64, v0
	v_xor_b32_e32 v2, 1, v220
	v_cmp_lt_i32_e32 vcc, v2, v0
	s_ashr_i32 s7, s6, 31
	s_lshl_b64 s[4:5], s[6:7], 11
	v_cndmask_b32_e32 v2, v220, v2, vcc
	v_lshlrev_b32_e32 v6, 2, v2
	v_xor_b32_e32 v2, 2, v220
	v_cmp_lt_i32_e32 vcc, v2, v0
	s_lshl_b64 s[2:3], s[6:7], 2
	v_mov_b32_e32 v3, s5
	v_cndmask_b32_e32 v2, v220, v2, vcc
	v_lshlrev_b32_e32 v7, 2, v2
	v_xor_b32_e32 v2, 4, v220
	v_cmp_lt_i32_e32 vcc, v2, v0
	v_cmp_eq_u32_e64 s[0:1], 0, v57
	s_nop 0
	v_cndmask_b32_e32 v2, v220, v2, vcc
	v_lshlrev_b32_e32 v8, 2, v2
	v_xor_b32_e32 v2, 8, v220
	v_cmp_lt_i32_e32 vcc, v2, v0
	s_nop 1
	v_cndmask_b32_e32 v2, v220, v2, vcc
	v_lshlrev_b32_e32 v9, 2, v2
	v_xor_b32_e32 v2, 16, v220
	v_cmp_lt_i32_e32 vcc, v2, v0
	s_nop 1
	v_cndmask_b32_e32 v2, v220, v2, vcc
	v_lshlrev_b32_e32 v10, 2, v2
	v_xor_b32_e32 v2, 32, v220
	v_cmp_lt_i32_e32 vcc, v2, v0
	s_nop 1
	v_cndmask_b32_e32 v0, v220, v2, vcc
	v_lshl_or_b32 v2, v57, 3, s4
	s_lshl_b64 s[4:5], s[6:7], 12
	v_readlane_b32 s7, v252, 57
	s_add_u32 s4, s7, s4
	v_readlane_b32 s7, v252, 58
	v_lshlrev_b32_e32 v11, 2, v0
	v_lshlrev_b32_e32 v0, 4, v57
	s_addc_u32 s5, s7, s5
	v_lshl_add_u64 v[4:5], s[4:5], 0, v[0:1]
	global_load_dwordx4 v[12:15], v[4:5], off offset:-3072
	global_load_dwordx4 v[16:19], v[4:5], off offset:-2048
	global_load_dwordx4 v[20:23], v[4:5], off offset:-1024
	global_load_dwordx4 v[24:27], v[4:5], off
	s_waitcnt vmcnt(0)
	s_branch .LBB0_625

.LBB0_625:
	s_waitcnt lgkmcnt(0)
	v_lshl_add_u64 v[30:31], s[40:41], 0, v[2:3]
	s_mov_b32 s4, 0x600000
	v_add_co_u32_e32 v28, vcc, s4, v30
	s_waitcnt vmcnt(5)
	v_cvt_pk_bf16_f32 v50, v12, v13
	v_addc_co_u32_e32 v29, vcc, 0, v31, vcc
	v_cvt_pk_bf16_f32 v51, v14, v15
	v_mul_f32_e32 v0, v13, v13
	v_fmac_f32_e32 v0, v12, v12
	v_fmac_f32_e32 v0, v14, v14
	v_fmac_f32_e32 v0, v15, v15
	v_cvt_pk_bf16_f32 v52, v16, v17
	v_cvt_pk_bf16_f32 v53, v18, v19
	v_mul_f32_e32 v60, v17, v17
	v_fmac_f32_e32 v60, v16, v16
	v_fmac_f32_e32 v60, v18, v18
	v_fmac_f32_e32 v60, v19, v19
	v_add_f32_e32 v0, v0, v60
	v_cvt_pk_bf16_f32 v54, v20, v21
	v_cvt_pk_bf16_f32 v55, v22, v23
	v_mul_f32_e32 v60, v21, v21
	v_fmac_f32_e32 v60, v20, v20
	v_fmac_f32_e32 v60, v22, v22
	v_fmac_f32_e32 v60, v23, v23
	v_add_f32_e32 v0, v0, v60
	v_cvt_pk_bf16_f32 v62, v24, v25
	v_cvt_pk_bf16_f32 v63, v26, v27
	v_mul_f32_e32 v60, v25, v25
	v_fmac_f32_e32 v60, v24, v24
	v_fmac_f32_e32 v60, v26, v26
	v_fmac_f32_e32 v60, v27, v27
	v_add_f32_e32 v0, v0, v60
	v_readlane_b32 s98, v254, 6
	s_nop 1
	s_add_i32 s98, s6, s98
	s_cmpk_gt_i32 s98, 0x3fff
	s_cbranch_scc1 .Lxb_nold
	v_lshl_add_u64 v[48:49], v[4:5], 0, s[10:11]
	global_load_dwordx4 v[12:15], v[48:49], off offset:-3072
	global_load_dwordx4 v[16:19], v[48:49], off offset:-2048
	global_load_dwordx4 v[20:23], v[48:49], off offset:-1024
	global_load_dwordx4 v[24:27], v[48:49], off
.Lxb_nold:
	global_store_dwordx2 v[28:29], v[50:51], off
	global_store_dwordx2 v[28:29], v[52:53], off offset:512
	global_store_dwordx2 v[28:29], v[54:55], off offset:1024
	global_store_dwordx2 v[28:29], v[62:63], off offset:1536
	ds_bpermute_b32 v60, v6, v0
	s_waitcnt lgkmcnt(0)
	v_add_f32_e32 v0, v0, v60
	ds_bpermute_b32 v60, v7, v0
	s_waitcnt lgkmcnt(0)
	v_add_f32_e32 v0, v0, v60
	ds_bpermute_b32 v60, v8, v0
	s_waitcnt lgkmcnt(0)
	v_add_f32_e32 v0, v0, v60
	ds_bpermute_b32 v60, v9, v0
	s_waitcnt lgkmcnt(0)
	v_add_f32_e32 v0, v0, v60
	ds_bpermute_b32 v60, v10, v0
	s_waitcnt lgkmcnt(0)
	v_add_f32_e32 v0, v0, v60
	ds_bpermute_b32 v60, v11, v0
	s_and_saveexec_b64 s[4:5], s[0:1]
	s_cbranch_execz .LBB0_624
	s_add_u32 s8, s40, s2
	s_waitcnt lgkmcnt(0)
	v_add_f32_e32 v0, v0, v60
	s_addc_u32 s9, s41, s3
	global_store_dword v1, v0, s[8:9]
	s_branch .LBB0_624
